# attention softmax: redundant canonicalising v_max around the row-max tree removed (4 VALU per tile per wave, bit-exact)
# speedup vs baseline: 1.0068x; 1.0068x over previous
.Latt_b_nod:
	s_cmp_gt_i32 s86, s9
	s_cbranch_scc1 .Latt_b_bar
	v_max_f32_e32 v176, v96, v80
	v_max3_f32 v177, v81, v98, v82
	v_max3_f32 v176, v176, v97, v99
	v_max3_f32 v177, v177, v100, v84
	v_max3_f32 v176, v176, v83, v101
	v_max3_f32 v177, v177, v102, v86
	v_max3_f32 v176, v176, v85, v103
	v_max3_f32 v177, v177, v104, v88
	v_max3_f32 v176, v176, v87, v105
	v_max3_f32 v177, v177, v106, v90
	v_max3_f32 v176, v176, v89, v107
	v_max3_f32 v177, v177, v108, v92
	v_max3_f32 v176, v176, v91, v109
	v_max3_f32 v177, v177, v110, v94
	v_max3_f32 v176, v176, v93, v111
	v_max3_f32 v176, v176, v95, v177
	v_mov_b32_e32 v177, v176
	s_nop 1
	v_permlane32_swap_b32_e32 v176, v177
	v_max_f32_e32 v176, v176, v177
	s_mov_b32 s4, 0x41000000
	v_cmp_lt_f32_e32 vcc, s4, v176
	s_cbranch_vccz .Latt_b_exp
	v_max_f32_e32 v64, v176, v176
	v_max_f32_e32 v66, 0, v64
	v_exp_f32_e64 v176, -v66
	v_add_f32_e32 v173, v173, v66
	v_xor_b32_e32 v64, 0x80000000, v173
	v_pk_add_f32 v[96:97], v[96:97], v[66:67] op_sel_hi:[1,0] neg_lo:[0,1] neg_hi:[0,1]
	v_pk_add_f32 v[80:81], v[80:81], v[66:67] op_sel_hi:[1,0] neg_lo:[0,1] neg_hi:[0,1]
	v_pk_add_f32 v[98:99], v[98:99], v[66:67] op_sel_hi:[1,0] neg_lo:[0,1] neg_hi:[0,1]
	v_pk_add_f32 v[82:83], v[82:83], v[66:67] op_sel_hi:[1,0] neg_lo:[0,1] neg_hi:[0,1]
	v_pk_add_f32 v[100:101], v[100:101], v[66:67] op_sel_hi:[1,0] neg_lo:[0,1] neg_hi:[0,1]
	v_pk_add_f32 v[84:85], v[84:85], v[66:67] op_sel_hi:[1,0] neg_lo:[0,1] neg_hi:[0,1]
	v_pk_add_f32 v[102:103], v[102:103], v[66:67] op_sel_hi:[1,0] neg_lo:[0,1] neg_hi:[0,1]
	v_pk_add_f32 v[86:87], v[86:87], v[66:67] op_sel_hi:[1,0] neg_lo:[0,1] neg_hi:[0,1]
	v_pk_add_f32 v[104:105], v[104:105], v[66:67] op_sel_hi:[1,0] neg_lo:[0,1] neg_hi:[0,1]
	v_pk_add_f32 v[88:89], v[88:89], v[66:67] op_sel_hi:[1,0] neg_lo:[0,1] neg_hi:[0,1]
	v_pk_add_f32 v[106:107], v[106:107], v[66:67] op_sel_hi:[1,0] neg_lo:[0,1] neg_hi:[0,1]
	v_pk_add_f32 v[90:91], v[90:91], v[66:67] op_sel_hi:[1,0] neg_lo:[0,1] neg_hi:[0,1]
	v_pk_add_f32 v[108:109], v[108:109], v[66:67] op_sel_hi:[1,0] neg_lo:[0,1] neg_hi:[0,1]
	v_pk_add_f32 v[92:93], v[92:93], v[66:67] op_sel_hi:[1,0] neg_lo:[0,1] neg_hi:[0,1]
	v_pk_add_f32 v[110:111], v[110:111], v[66:67] op_sel_hi:[1,0] neg_lo:[0,1] neg_hi:[0,1]
	v_pk_add_f32 v[94:95], v[94:95], v[66:67] op_sel_hi:[1,0] neg_lo:[0,1] neg_hi:[0,1]
	v_mov_b32_e32 v65, v64
	v_mov_b32_e32 v66, v64
	v_mov_b32_e32 v67, v64
	v_mov_b32_e32 v68, v64
	v_mov_b32_e32 v69, v64
	v_mov_b32_e32 v70, v64
	v_mov_b32_e32 v71, v64
	v_mov_b32_e32 v72, v64
	v_mov_b32_e32 v73, v64
	v_mov_b32_e32 v74, v64
	v_mov_b32_e32 v75, v64
	v_mov_b32_e32 v76, v64
	v_mov_b32_e32 v77, v64
	v_mov_b32_e32 v78, v64
	v_mov_b32_e32 v79, v64
	v_pk_mul_f32 v[46:47], v[46:47], v[176:177] op_sel_hi:[1,0]
	v_pk_mul_f32 v[44:45], v[44:45], v[176:177] op_sel_hi:[1,0]
	v_pk_mul_f32 v[42:43], v[42:43], v[176:177] op_sel_hi:[1,0]
	v_pk_mul_f32 v[40:41], v[40:41], v[176:177] op_sel_hi:[1,0]
	v_pk_mul_f32 v[38:39], v[38:39], v[176:177] op_sel_hi:[1,0]
	v_pk_mul_f32 v[36:37], v[36:37], v[176:177] op_sel_hi:[1,0]
	v_pk_mul_f32 v[34:35], v[34:35], v[176:177] op_sel_hi:[1,0]
	v_pk_mul_f32 v[32:33], v[32:33], v[176:177] op_sel_hi:[1,0]
	v_pk_mul_f32 v[30:31], v[30:31], v[176:177] op_sel_hi:[1,0]
	v_pk_mul_f32 v[28:29], v[28:29], v[176:177] op_sel_hi:[1,0]
	v_pk_mul_f32 v[26:27], v[26:27], v[176:177] op_sel_hi:[1,0]
	v_pk_mul_f32 v[24:25], v[24:25], v[176:177] op_sel_hi:[1,0]
	v_pk_mul_f32 v[22:23], v[22:23], v[176:177] op_sel_hi:[1,0]
	v_pk_mul_f32 v[20:21], v[20:21], v[176:177] op_sel_hi:[1,0]
	v_pk_mul_f32 v[18:19], v[18:19], v[176:177] op_sel_hi:[1,0]
	v_pk_mul_f32 v[16:17], v[16:17], v[176:177] op_sel_hi:[1,0]
	v_pk_mul_f32 v[14:15], v[14:15], v[176:177] op_sel_hi:[1,0]
	v_pk_mul_f32 v[12:13], v[12:13], v[176:177] op_sel_hi:[1,0]
	v_pk_mul_f32 v[10:11], v[10:11], v[176:177] op_sel_hi:[1,0]
	v_pk_mul_f32 v[8:9], v[8:9], v[176:177] op_sel_hi:[1,0]
	v_pk_mul_f32 v[6:7], v[6:7], v[176:177] op_sel_hi:[1,0]
	v_pk_mul_f32 v[4:5], v[4:5], v[176:177] op_sel_hi:[1,0]
	v_pk_mul_f32 v[2:3], v[2:3], v[176:177] op_sel_hi:[1,0]
	v_pk_mul_f32 v[0:1], v[0:1], v[176:177] op_sel_hi:[1,0]
	v_pk_mul_f32 v[62:63], v[62:63], v[176:177] op_sel_hi:[1,0]
	v_pk_mul_f32 v[60:61], v[60:61], v[176:177] op_sel_hi:[1,0]
	v_pk_mul_f32 v[58:59], v[58:59], v[176:177] op_sel_hi:[1,0]
	v_pk_mul_f32 v[56:57], v[56:57], v[176:177] op_sel_hi:[1,0]
	v_pk_mul_f32 v[54:55], v[54:55], v[176:177] op_sel_hi:[1,0]
	v_pk_mul_f32 v[52:53], v[52:53], v[176:177] op_sel_hi:[1,0]
	v_pk_mul_f32 v[50:51], v[50:51], v[176:177] op_sel_hi:[1,0]
	v_pk_mul_f32 v[48:49], v[48:49], v[176:177] op_sel_hi:[1,0]
	v_mul_f32_e32 v172, v172, v176

.Latt_a_nod:
	s_nop 9
	v_max_f32_e32 v176, v96, v80
	v_max3_f32 v177, v81, v98, v82
	v_max3_f32 v176, v176, v97, v99
	v_max3_f32 v177, v177, v100, v84
	v_max3_f32 v176, v176, v83, v101
	v_max3_f32 v177, v177, v102, v86
	v_max3_f32 v176, v176, v85, v103
	v_max3_f32 v177, v177, v104, v88
	v_max3_f32 v176, v176, v87, v105
	v_max3_f32 v177, v177, v106, v90
	v_max3_f32 v176, v176, v89, v107
	v_max3_f32 v177, v177, v108, v92
	v_max3_f32 v176, v176, v91, v109
	v_max3_f32 v177, v177, v110, v94
	v_max3_f32 v176, v176, v93, v111
	v_max3_f32 v176, v176, v95, v177
	v_mov_b32_e32 v177, v176
	s_nop 1
	v_permlane32_swap_b32_e32 v176, v177
	v_max_f32_e32 v176, v176, v177
	s_mov_b32 s4, 0x41000000
	v_cmp_lt_f32_e32 vcc, s4, v176
	s_cbranch_vccz .Latt_a_exp
	v_max_f32_e32 v64, v176, v176
	v_max_f32_e32 v66, 0, v64
	v_exp_f32_e64 v176, -v66
	v_add_f32_e32 v173, v173, v66
	v_xor_b32_e32 v64, 0x80000000, v173
	v_pk_add_f32 v[96:97], v[96:97], v[66:67] op_sel_hi:[1,0] neg_lo:[0,1] neg_hi:[0,1]
	v_pk_add_f32 v[80:81], v[80:81], v[66:67] op_sel_hi:[1,0] neg_lo:[0,1] neg_hi:[0,1]
	v_pk_add_f32 v[98:99], v[98:99], v[66:67] op_sel_hi:[1,0] neg_lo:[0,1] neg_hi:[0,1]
	v_pk_add_f32 v[82:83], v[82:83], v[66:67] op_sel_hi:[1,0] neg_lo:[0,1] neg_hi:[0,1]
	v_pk_add_f32 v[100:101], v[100:101], v[66:67] op_sel_hi:[1,0] neg_lo:[0,1] neg_hi:[0,1]
	v_pk_add_f32 v[84:85], v[84:85], v[66:67] op_sel_hi:[1,0] neg_lo:[0,1] neg_hi:[0,1]
	v_pk_add_f32 v[102:103], v[102:103], v[66:67] op_sel_hi:[1,0] neg_lo:[0,1] neg_hi:[0,1]
	v_pk_add_f32 v[86:87], v[86:87], v[66:67] op_sel_hi:[1,0] neg_lo:[0,1] neg_hi:[0,1]
	v_pk_add_f32 v[104:105], v[104:105], v[66:67] op_sel_hi:[1,0] neg_lo:[0,1] neg_hi:[0,1]
	v_pk_add_f32 v[88:89], v[88:89], v[66:67] op_sel_hi:[1,0] neg_lo:[0,1] neg_hi:[0,1]
	v_pk_add_f32 v[106:107], v[106:107], v[66:67] op_sel_hi:[1,0] neg_lo:[0,1] neg_hi:[0,1]
	v_pk_add_f32 v[90:91], v[90:91], v[66:67] op_sel_hi:[1,0] neg_lo:[0,1] neg_hi:[0,1]
	v_pk_add_f32 v[108:109], v[108:109], v[66:67] op_sel_hi:[1,0] neg_lo:[0,1] neg_hi:[0,1]
	v_pk_add_f32 v[92:93], v[92:93], v[66:67] op_sel_hi:[1,0] neg_lo:[0,1] neg_hi:[0,1]
	v_pk_add_f32 v[110:111], v[110:111], v[66:67] op_sel_hi:[1,0] neg_lo:[0,1] neg_hi:[0,1]
	v_pk_add_f32 v[94:95], v[94:95], v[66:67] op_sel_hi:[1,0] neg_lo:[0,1] neg_hi:[0,1]
	v_mov_b32_e32 v65, v64
	v_mov_b32_e32 v66, v64
	v_mov_b32_e32 v67, v64
	v_mov_b32_e32 v68, v64
	v_mov_b32_e32 v69, v64
	v_mov_b32_e32 v70, v64
	v_mov_b32_e32 v71, v64
	v_mov_b32_e32 v72, v64
	v_mov_b32_e32 v73, v64
	v_mov_b32_e32 v74, v64
	v_mov_b32_e32 v75, v64
	v_mov_b32_e32 v76, v64
	v_mov_b32_e32 v77, v64
	v_mov_b32_e32 v78, v64
	v_mov_b32_e32 v79, v64
	v_pk_mul_f32 v[46:47], v[46:47], v[176:177] op_sel_hi:[1,0]
	v_pk_mul_f32 v[44:45], v[44:45], v[176:177] op_sel_hi:[1,0]
	v_pk_mul_f32 v[42:43], v[42:43], v[176:177] op_sel_hi:[1,0]
	v_pk_mul_f32 v[40:41], v[40:41], v[176:177] op_sel_hi:[1,0]
	v_pk_mul_f32 v[38:39], v[38:39], v[176:177] op_sel_hi:[1,0]
	v_pk_mul_f32 v[36:37], v[36:37], v[176:177] op_sel_hi:[1,0]
	v_pk_mul_f32 v[34:35], v[34:35], v[176:177] op_sel_hi:[1,0]
	v_pk_mul_f32 v[32:33], v[32:33], v[176:177] op_sel_hi:[1,0]
	v_pk_mul_f32 v[30:31], v[30:31], v[176:177] op_sel_hi:[1,0]
	v_pk_mul_f32 v[28:29], v[28:29], v[176:177] op_sel_hi:[1,0]
	v_pk_mul_f32 v[26:27], v[26:27], v[176:177] op_sel_hi:[1,0]
	v_pk_mul_f32 v[24:25], v[24:25], v[176:177] op_sel_hi:[1,0]
	v_pk_mul_f32 v[22:23], v[22:23], v[176:177] op_sel_hi:[1,0]
	v_pk_mul_f32 v[20:21], v[20:21], v[176:177] op_sel_hi:[1,0]
	v_pk_mul_f32 v[18:19], v[18:19], v[176:177] op_sel_hi:[1,0]
	v_pk_mul_f32 v[16:17], v[16:17], v[176:177] op_sel_hi:[1,0]
	v_pk_mul_f32 v[14:15], v[14:15], v[176:177] op_sel_hi:[1,0]
	v_pk_mul_f32 v[12:13], v[12:13], v[176:177] op_sel_hi:[1,0]
	v_pk_mul_f32 v[10:11], v[10:11], v[176:177] op_sel_hi:[1,0]
	v_pk_mul_f32 v[8:9], v[8:9], v[176:177] op_sel_hi:[1,0]
	v_pk_mul_f32 v[6:7], v[6:7], v[176:177] op_sel_hi:[1,0]
	v_pk_mul_f32 v[4:5], v[4:5], v[176:177] op_sel_hi:[1,0]
	v_pk_mul_f32 v[2:3], v[2:3], v[176:177] op_sel_hi:[1,0]
	v_pk_mul_f32 v[0:1], v[0:1], v[176:177] op_sel_hi:[1,0]
	v_pk_mul_f32 v[62:63], v[62:63], v[176:177] op_sel_hi:[1,0]
	v_pk_mul_f32 v[60:61], v[60:61], v[176:177] op_sel_hi:[1,0]
	v_pk_mul_f32 v[58:59], v[58:59], v[176:177] op_sel_hi:[1,0]
	v_pk_mul_f32 v[56:57], v[56:57], v[176:177] op_sel_hi:[1,0]
	v_pk_mul_f32 v[54:55], v[54:55], v[176:177] op_sel_hi:[1,0]
	v_pk_mul_f32 v[52:53], v[52:53], v[176:177] op_sel_hi:[1,0]
	v_pk_mul_f32 v[50:51], v[50:51], v[176:177] op_sel_hi:[1,0]
	v_pk_mul_f32 v[48:49], v[48:49], v[176:177] op_sel_hi:[1,0]
	v_mul_f32_e32 v172, v172, v176
